# mix sample rows stored fragment-major (MFMA lane order) by the P2 sample items so phase3_sample's 8 A-fragment loads are 1 KB contiguous each
# speedup vs baseline: 1.0308x; 1.0018x over previous
.LBB0_789:
	s_or_b64 exec, exec, s[2:3]
	v_readlane_b32 s2, v242, 9
	s_waitcnt lgkmcnt(0)
	s_barrier
	v_mov_b32_e32 v2, s2
	v_readlane_b32 s2, v242, 10
	s_nop 1
	v_mov_b32_e32 v3, s2
	v_readlane_b32 s2, v242, 11
	ds_read_b128 v[6:9], v2
	ds_read_b128 v[2:5], v3
	v_mov_b32_e32 v10, s2
	v_readlane_b32 s2, v242, 12
	s_nop 1
	v_mov_b32_e32 v11, s2
	v_readlane_b32 s2, v242, 13
	ds_read_b128 v[14:17], v10
	ds_read_b128 v[10:13], v11
	v_mov_b32_e32 v18, s2
	v_readlane_b32 s2, v242, 14
	s_nop 1
	v_mov_b32_e32 v19, s2
	v_readlane_b32 s2, v242, 15
	ds_read_b128 v[22:25], v18
	ds_read_b128 v[18:21], v19
	v_mov_b32_e32 v26, s2
	v_readlane_b32 s2, v242, 16
	s_nop 1
	v_mov_b32_e32 v27, s2
	v_readlane_b32 s2, v242, 17
	ds_read_b128 v[30:33], v26
	ds_read_b128 v[26:29], v27
	v_mov_b32_e32 v34, s2
	v_readlane_b32 s2, v242, 18
	s_nop 1
	v_mov_b32_e32 v35, s2
	v_readlane_b32 s2, v242, 19
	ds_read_b128 v[38:41], v34
	ds_read_b128 v[34:37], v35
	v_mov_b32_e32 v42, s2
	v_readlane_b32 s2, v242, 20
	s_nop 1
	v_mov_b32_e32 v43, s2
	v_readlane_b32 s2, v242, 21
	ds_read_b128 v[46:49], v42
	ds_read_b128 v[42:45], v43
	v_mov_b32_e32 v50, s2
	v_readlane_b32 s2, v242, 22
	s_nop 1
	v_mov_b32_e32 v51, s2
	v_readlane_b32 s2, v242, 23
	ds_read_b128 v[54:57], v50
	ds_read_b128 v[50:53], v51
	v_mov_b32_e32 v58, s2
	v_readlane_b32 s2, v242, 24
	s_nop 1
	v_mov_b32_e32 v59, s2
	ds_read_b128 v[62:65], v58
	ds_read_b128 v[58:61], v59
	s_and_saveexec_b64 s[34:35], s[42:43]
	s_cbranch_execz .LBB0_791
	v_lshlrev_b64 v[176:177], 2, v[172:173]
	v_lshl_add_u64 v[178:179], s[80:81], 0, v[176:177]
	v_lshl_add_u64 v[176:177], s[82:83], 0, v[176:177]
	global_load_dword v190, v[178:179], off
	global_load_dword v189, v[176:177], off
	v_readlane_b32 s2, v242, 25
	s_mov_b32 s12, 0x3b2aaaab
	s_nop 0
	v_mov_b32_e32 v90, s2
	v_readlane_b32 s2, v242, 26
	ds_read_b128 v[90:93], v90
	s_nop 0
	v_mov_b32_e32 v94, s2
	v_readlane_b32 s2, v242, 27
	ds_read_b128 v[94:97], v94
	s_waitcnt lgkmcnt(0)
	v_mov_b32_e32 v176, v94
	v_mov_b32_e32 v98, s2
	v_readlane_b32 s2, v242, 28
	ds_read_b128 v[98:101], v98
	s_nop 0
	v_mov_b32_e32 v102, s2
	v_readlane_b32 s2, v242, 29
	ds_read_b128 v[102:105], v102
	s_nop 0
	v_mov_b32_e32 v106, s2
	v_readlane_b32 s2, v242, 30
	ds_read_b128 v[106:109], v106
	s_nop 0
	v_mov_b32_e32 v110, s2
	v_readlane_b32 s2, v242, 31
	ds_read_b128 v[110:113], v110
	s_nop 0
	v_mov_b32_e32 v114, s2
	v_readlane_b32 s2, v242, 32
	ds_read_b128 v[114:117], v114
	s_nop 0
	v_mov_b32_e32 v118, s2
	s_add_i32 s2, 32, 0x16000
	v_mov_b32_e32 v122, s2
	v_readlane_b32 s2, v242, 33
	ds_read_b128 v[122:125], v122
	ds_read_b128 v[118:121], v118
	v_mov_b32_e32 v126, s2
	v_readlane_b32 s2, v242, 34
	ds_read_b128 v[126:129], v126
	s_waitcnt lgkmcnt(0)
	v_mov_b32_e32 v177, v126
	v_mov_b32_e32 v130, s2
	v_readlane_b32 s2, v242, 35
	ds_read_b128 v[130:133], v130
	v_mov_b32_e32 v126, v95
	v_mov_b32_e32 v134, s2
	v_readlane_b32 s2, v242, 36
	ds_read_b128 v[134:137], v134
	s_nop 0
	v_mov_b32_e32 v138, s2
	v_readlane_b32 s2, v242, 37
	ds_read_b128 v[138:141], v138
	s_nop 0
	v_mov_b32_e32 v142, s2
	v_readlane_b32 s2, v242, 38
	ds_read_b128 v[142:145], v142
	s_nop 0
	v_mov_b32_e32 v146, s2
	v_readlane_b32 s2, v242, 39
	ds_read_b128 v[146:149], v146
	s_nop 0
	v_mov_b32_e32 v150, s2
	v_readlane_b32 s2, v242, 40
	s_mulk_i32 s2, 0x300
	ds_read_b128 v[150:153], v150
	v_add_u32_e32 v172, s2, v172
	v_ashrrev_i32_e32 v173, 31, v172
	v_lshl_add_u64 v[172:173], v[172:173], 2, s[84:85]
	global_load_dword v186, v[172:173], off
	global_load_dword v188, v[172:173], off offset:1536
	global_load_dword v187, v[172:173], off offset:3072
	v_mov_b32_e32 v172, v90
	v_mov_b32_e32 v173, v122
	v_pk_add_f32 v[172:173], v[172:173], 0 op_sel_hi:[1,0]
	s_movk_i32 s2, 0xd000
	v_pk_add_f32 v[172:173], v[172:173], v[176:177]
	v_mov_b32_e32 v176, v98
	s_waitcnt lgkmcnt(5)
	v_mov_b32_e32 v177, v130
	v_pk_add_f32 v[172:173], v[172:173], v[176:177]
	v_mov_b32_e32 v176, v102
	s_waitcnt lgkmcnt(4)
	v_mov_b32_e32 v177, v134
	v_pk_add_f32 v[172:173], v[172:173], v[176:177]
	v_mov_b32_e32 v176, v106
	s_waitcnt lgkmcnt(3)
	v_mov_b32_e32 v177, v138
	v_pk_add_f32 v[172:173], v[172:173], v[176:177]
	v_mov_b32_e32 v176, v110
	s_waitcnt lgkmcnt(2)
	v_mov_b32_e32 v177, v142
	v_pk_add_f32 v[172:173], v[172:173], v[176:177]
	v_mov_b32_e32 v176, v114
	s_waitcnt lgkmcnt(1)
	v_mov_b32_e32 v177, v146
	v_pk_add_f32 v[172:173], v[172:173], v[176:177]
	v_mov_b32_e32 v176, v118
	s_waitcnt lgkmcnt(0)
	v_mov_b32_e32 v177, v150
	v_pk_add_f32 v[172:173], v[172:173], v[176:177]
	v_lshlrev_b64 v[176:177], 1, v[164:165]
	v_pk_mul_f32 v[172:173], v[172:173], s[12:13] op_sel_hi:[1,0]
	v_mov_b32_e32 v122, v91
	v_fma_f32 v90, -v173, v173, v172
	v_max_f32_e32 v90, 0, v90
	v_add_f32_e32 v90, 0x358637bd, v90
	v_cmp_gt_f32_e32 vcc, s33, v90
	v_mul_f32_e32 v94, 0x4b800000, v90
	v_mov_b32_e32 v130, v99
	v_cndmask_b32_e32 v90, v90, v94, vcc
	v_rsq_f32_e32 v90, v90
	v_mov_b32_e32 v134, v103
	v_mov_b32_e32 v138, v107
	v_mov_b32_e32 v142, v111
	v_mul_f32_e32 v94, 0x45800000, v90
	v_cndmask_b32_e32 v90, v90, v94, vcc
	v_sub_f32_e32 v94, v174, v173
	v_mul_f32_e32 v90, v94, v90
	s_waitcnt vmcnt(3)
	v_fma_f32 v90, v190, v90, v189
	v_mul_f32_e32 v94, 0xbfb8aa3b, v90
	v_exp_f32_e32 v94, v94
	v_lshl_add_u64 v[172:173], s[30:31], 0, v[176:177]
	v_add_co_u32_e32 v178, vcc, s2, v172
	v_add_f32_e32 v94, 1.0, v94
	v_rcp_f32_e32 v94, v94
	v_addc_co_u32_e32 v179, vcc, -1, v173, vcc
	v_lshl_add_u64 v[176:177], s[10:11], 0, v[176:177]
	v_mul_f32_e32 v90, v90, v94
	v_mov_b32_e32 v146, v115
	v_mov_b32_e32 v150, v119
	s_movk_i32 s2, 0xe000
	s_waitcnt vmcnt(0)
	v_lshlrev_b32_e32 v94, 16, v192
	v_mul_f32_e32 v90, v90, v94
	v_bfe_u32 v94, v90, 16, 1
	v_add3_u32 v90, v90, v94, s15
	v_lshrrev_b32_e64 v245, 3, s7
	v_lshlrev_b32_e32 v245, 16, v245
	v_and_b32_e64 v246, s7, 7
	v_lshl_add_u32 v245, v246, 6, v245
	v_add_u32_e32 v245, 0x2000000, v245
	v_mov_b32_e32 v247, 0
	v_mov_b32_e32 v252, v0
	v_lshrrev_b32_e32 v246, 7, v252
	v_lshl_add_u32 v246, v246, 13, v245
	v_bfe_u32 v253, v252, 4, 3
	v_lshl_add_u32 v246, v253, 10, v246
	v_bfe_u32 v253, v252, 3, 1
	v_lshl_add_u32 v246, v253, 9, v246
	v_and_b32_e32 v253, 7, v252
	v_lshl_add_u32 v246, v253, 1, v246
	v_lshl_add_u64 v[236:237], s[62:63], 0, v[246:247]
	v_add_u32_e32 v252, 0x180, v0
	v_lshrrev_b32_e32 v246, 7, v252
	v_lshl_add_u32 v246, v246, 13, v245
	v_bfe_u32 v253, v252, 4, 3
	v_lshl_add_u32 v246, v253, 10, v246
	v_bfe_u32 v253, v252, 3, 1
	v_lshl_add_u32 v246, v253, 9, v246
	v_and_b32_e32 v253, 7, v252
	v_lshl_add_u32 v246, v253, 1, v246
	v_lshl_add_u64 v[238:239], s[62:63], 0, v[246:247]
	v_add_u32_e32 v252, 0x300, v0
	v_lshrrev_b32_e32 v246, 7, v252
	v_lshl_add_u32 v246, v246, 13, v245
	v_bfe_u32 v253, v252, 4, 3
	v_lshl_add_u32 v246, v253, 10, v246
	v_bfe_u32 v253, v252, 3, 1
	v_lshl_add_u32 v246, v253, 9, v246
	v_and_b32_e32 v253, 7, v252
	v_lshl_add_u32 v246, v253, 1, v246
	v_lshl_add_u64 v[240:241], s[62:63], 0, v[246:247]
	global_store_short_d16_hi v[236:237], v90, off
	v_mul_f32_e32 v90, v185, v188
	v_fmac_f32_e32 v90, v191, v186
	v_fmac_f32_e32 v90, v184, v187
	v_lshlrev_b32_e32 v94, 16, v193
	v_mul_f32_e32 v90, v90, v94
	v_bfe_u32 v94, v90, 16, 1
	v_add3_u32 v90, v90, v94, s15
	global_store_short_d16_hi v[238:239], v90, off
	v_pk_add_f32 v[90:91], v[122:123], 0 op_sel_hi:[1,0]
	s_nop 0
	v_pk_add_f32 v[90:91], v[90:91], v[126:127]
	s_nop 0
	v_pk_add_f32 v[90:91], v[90:91], v[130:131]
	s_nop 0
	v_pk_add_f32 v[90:91], v[90:91], v[134:135]
	s_nop 0
	v_pk_add_f32 v[90:91], v[90:91], v[138:139]
	s_nop 0
	v_pk_add_f32 v[90:91], v[90:91], v[142:143]
	s_nop 0
	v_pk_add_f32 v[90:91], v[90:91], v[146:147]
	s_nop 0
	v_pk_add_f32 v[90:91], v[90:91], v[150:151]
	s_nop 0
	v_pk_mul_f32 v[90:91], v[90:91], s[12:13] op_sel_hi:[1,0]
	s_nop 0
	v_fma_f32 v90, -v91, v91, v90
	v_max_f32_e32 v90, 0, v90
	v_add_f32_e32 v90, 0x358637bd, v90
	v_cmp_gt_f32_e32 vcc, s33, v90
	v_mul_f32_e32 v94, 0x4b800000, v90
	v_sub_f32_e32 v91, v175, v91
	v_cndmask_b32_e32 v90, v90, v94, vcc
	v_rsq_f32_e32 v90, v90
	s_nop 0
	v_mul_f32_e32 v94, 0x45800000, v90
	v_cndmask_b32_e32 v90, v90, v94, vcc
	v_mul_f32_e32 v90, v91, v90
	v_fma_f32 v90, v190, v90, v189
	v_mul_f32_e32 v91, 0xbfb8aa3b, v90
	v_exp_f32_e32 v91, v91
	s_nop 0
	v_add_f32_e32 v91, 1.0, v91
	v_rcp_f32_e32 v91, v91
	s_nop 0
	v_mul_f32_e32 v94, v90, v91
	v_add_co_u32_e32 v90, vcc, s2, v172
	s_movk_i32 s2, 0xf000
	s_nop 0
	v_addc_co_u32_e32 v91, vcc, -1, v173, vcc
	v_lshlrev_b32_e32 v95, 16, v194
	v_mul_f32_e32 v94, v94, v95
	v_bfe_u32 v95, v94, 16, 1
	v_add3_u32 v94, v94, v95, s15
	global_store_short_d16_hi v[236:237], v94, off offset:16
	v_mul_f32_e32 v94, v184, v188
	v_fmac_f32_e32 v94, v185, v186
	v_fmac_f32_e32 v94, v183, v187
	v_mov_b32_e32 v95, v128
	v_mov_b32_e32 v128, v97
	v_lshlrev_b32_e32 v90, 16, v195
	v_mul_f32_e32 v90, v94, v90
	v_bfe_u32 v91, v90, 16, 1
	v_add3_u32 v90, v90, v91, s15
	global_store_short_d16_hi v[238:239], v90, off offset:16
	v_mov_b32_e32 v90, v92
	v_mov_b32_e32 v91, v124
	v_pk_add_f32 v[90:91], v[90:91], 0 op_sel_hi:[1,0]
	v_mov_b32_e32 v94, v96
	v_pk_add_f32 v[90:91], v[90:91], v[94:95]
	v_mov_b32_e32 v94, v100
	v_mov_b32_e32 v95, v132
	v_pk_add_f32 v[90:91], v[90:91], v[94:95]
	v_mov_b32_e32 v94, v104
	v_mov_b32_e32 v95, v136
	v_pk_add_f32 v[90:91], v[90:91], v[94:95]
	v_mov_b32_e32 v94, v108
	v_mov_b32_e32 v95, v140
	v_pk_add_f32 v[90:91], v[90:91], v[94:95]
	v_mov_b32_e32 v94, v112
	v_mov_b32_e32 v95, v144
	v_pk_add_f32 v[90:91], v[90:91], v[94:95]
	v_mov_b32_e32 v94, v116
	v_mov_b32_e32 v95, v148
	v_pk_add_f32 v[90:91], v[90:91], v[94:95]
	v_mov_b32_e32 v94, v120
	v_mov_b32_e32 v95, v152
	v_pk_add_f32 v[90:91], v[90:91], v[94:95]
	v_mov_b32_e32 v124, v93
	v_pk_mul_f32 v[90:91], v[90:91], s[12:13] op_sel_hi:[1,0]
	v_mov_b32_e32 v132, v101
	v_fma_f32 v90, -v91, v91, v90
	v_max_f32_e32 v90, 0, v90
	v_add_f32_e32 v90, 0x358637bd, v90
	v_cmp_gt_f32_e32 vcc, s33, v90
	v_mul_f32_e32 v92, 0x4b800000, v90
	v_sub_f32_e32 v91, v170, v91
	v_cndmask_b32_e32 v90, v90, v92, vcc
	v_rsq_f32_e32 v90, v90
	v_mov_b32_e32 v136, v105
	v_mov_b32_e32 v140, v109
	v_mov_b32_e32 v144, v113
	v_mul_f32_e32 v92, 0x45800000, v90
	v_cndmask_b32_e32 v90, v90, v92, vcc
	v_mul_f32_e32 v90, v91, v90
	v_fma_f32 v90, v90, v190, v189
	v_mul_f32_e32 v91, 0xbfb8aa3b, v90
	v_exp_f32_e32 v91, v91
	v_add_co_u32_e32 v94, vcc, s2, v172
	s_movk_i32 s2, 0x1000
	v_add_f32_e32 v91, 1.0, v91
	v_rcp_f32_e32 v91, v91
	v_addc_co_u32_e32 v95, vcc, -1, v173, vcc
	v_mov_b32_e32 v148, v117
	v_mul_f32_e32 v90, v90, v91
	v_mov_b32_e32 v152, v121
	v_lshlrev_b32_e32 v91, 16, v196
	v_mul_f32_e32 v90, v90, v91
	v_bfe_u32 v91, v90, 16, 1
	v_add3_u32 v92, v90, v91, s15
	v_add_co_u32_e32 v90, vcc, s2, v176
	s_add_i32 s2, s4, s7
	s_nop 0
	v_addc_co_u32_e32 v91, vcc, 0, v177, vcc
	global_store_short_d16_hi v[236:237], v92, off offset:32
	v_mul_f32_e32 v92, v183, v188
	v_fmac_f32_e32 v92, v184, v186
	v_fmac_f32_e32 v92, v182, v187
	s_mul_hi_i32 s3, s2, 0xc00
	s_mulk_i32 s2, 0xc00
	s_add_u32 s2, s50, s2
	s_addc_u32 s3, s51, s3
	v_lshlrev_b32_e32 v94, 16, v197
	v_mul_f32_e32 v92, v92, v94
	v_bfe_u32 v94, v92, 16, 1
	v_add3_u32 v92, v92, v94, s15
	global_store_short_d16_hi v[238:239], v92, off offset:32
	v_pk_add_f32 v[92:93], v[124:125], 0 op_sel_hi:[1,0]
	s_nop 0
	v_pk_add_f32 v[92:93], v[92:93], v[128:129]
	s_nop 0
	v_pk_add_f32 v[92:93], v[92:93], v[132:133]
	s_nop 0
	v_pk_add_f32 v[92:93], v[92:93], v[136:137]
	s_nop 0
	v_pk_add_f32 v[92:93], v[92:93], v[140:141]
	s_nop 0
	v_pk_add_f32 v[92:93], v[92:93], v[144:145]
	s_nop 0
	v_pk_add_f32 v[92:93], v[92:93], v[148:149]
	s_nop 0
	v_pk_add_f32 v[92:93], v[92:93], v[152:153]
	s_nop 0
	v_pk_mul_f32 v[92:93], v[92:93], s[12:13] op_sel_hi:[1,0]
	s_nop 0
	v_fma_f32 v92, -v93, v93, v92
	v_max_f32_e32 v92, 0, v92
	v_add_f32_e32 v92, 0x358637bd, v92
	v_cmp_gt_f32_e32 vcc, s33, v92
	v_mul_f32_e32 v94, 0x4b800000, v92
	v_sub_f32_e32 v93, v171, v93
	v_cndmask_b32_e32 v92, v92, v94, vcc
	v_rsq_f32_e32 v92, v92
	s_nop 0
	v_mul_f32_e32 v94, 0x45800000, v92
	v_cndmask_b32_e32 v92, v92, v94, vcc
	v_mul_f32_e32 v92, v93, v92
	v_fmac_f32_e32 v189, v92, v190
	v_mul_f32_e32 v92, 0xbfb8aa3b, v189
	v_exp_f32_e32 v92, v92
	v_lshlrev_b32_e32 v93, 16, v198
	v_add_f32_e32 v92, 1.0, v92
	v_rcp_f32_e32 v92, v92
	s_nop 0
	v_mul_f32_e32 v92, v189, v92
	v_mul_f32_e32 v92, v92, v93
	v_bfe_u32 v93, v92, 16, 1
	v_add3_u32 v92, v92, v93, s15
	global_store_short_d16_hi v[236:237], v92, off offset:48
	v_mul_f32_e32 v92, v182, v188
	v_fmac_f32_e32 v92, v183, v186
	v_fmac_f32_e32 v92, v154, v187
	v_lshlrev_b32_e32 v93, 16, v199
	v_mul_f32_e32 v92, v92, v93
	v_bfe_u32 v93, v92, 16, 1
	v_add3_u32 v92, v92, v93, s15
	global_store_short_d16_hi v[238:239], v92, off offset:48
	v_lshl_add_u64 v[90:91], v[164:165], 2, s[2:3]
	v_add_co_u32_e32 v90, vcc, 0x4e00000, v90
	s_nop 1
	v_addc_co_u32_e32 v91, vcc, 0, v91, vcc
	global_store_dword v[90:91], v182, off
	global_store_dword v[90:91], v154, off offset:1536
.LBB0_791:
	s_or_b64 exec, exec, s[34:35]
	s_and_saveexec_b64 s[12:13], s[40:41]
	s_cbranch_execz .LBB0_782
	s_waitcnt lgkmcnt(7)
	v_mov_b32_e32 v90, v38
	v_mov_b32_e32 v91, v6
	v_mov_b32_e32 v6, v39
	v_pk_add_f32 v[90:91], v[90:91], 0 op_sel_hi:[1,0]
	s_waitcnt lgkmcnt(6)
	v_mov_b32_e32 v92, v34
	v_mov_b32_e32 v93, v2
	v_pk_add_f32 v[6:7], v[6:7], 0 op_sel_hi:[1,0]
	v_mov_b32_e32 v2, v35
	v_pk_add_f32 v[90:91], v[90:91], v[92:93]
	s_waitcnt lgkmcnt(5)
	v_mov_b32_e32 v92, v46
	v_mov_b32_e32 v93, v14
	v_pk_add_f32 v[2:3], v[6:7], v[2:3]
	v_mov_b32_e32 v14, v47
	v_pk_add_f32 v[90:91], v[90:91], v[92:93]
	s_waitcnt lgkmcnt(4)
	v_mov_b32_e32 v92, v42
	v_mov_b32_e32 v93, v10
	v_pk_add_f32 v[2:3], v[2:3], v[14:15]
	v_mov_b32_e32 v10, v43
	v_pk_add_f32 v[90:91], v[90:91], v[92:93]
	s_waitcnt lgkmcnt(3)
	v_mov_b32_e32 v92, v54
	v_mov_b32_e32 v93, v22
	v_pk_add_f32 v[2:3], v[2:3], v[10:11]
	v_mov_b32_e32 v22, v55
	v_pk_add_f32 v[90:91], v[90:91], v[92:93]
	s_waitcnt lgkmcnt(2)
	v_mov_b32_e32 v92, v50
	v_mov_b32_e32 v93, v18
	v_pk_add_f32 v[2:3], v[2:3], v[22:23]
	v_mov_b32_e32 v18, v51
	v_pk_add_f32 v[90:91], v[90:91], v[92:93]
	s_waitcnt lgkmcnt(1)
	v_mov_b32_e32 v92, v62
	v_mov_b32_e32 v93, v30
	v_pk_add_f32 v[2:3], v[2:3], v[18:19]
	v_mov_b32_e32 v30, v63
	v_pk_add_f32 v[90:91], v[90:91], v[92:93]
	v_mov_b32_e32 v93, v26
	v_pk_add_f32 v[2:3], v[2:3], v[30:31]
	s_waitcnt lgkmcnt(0)
	v_mov_b32_e32 v26, v59
	v_pk_add_f32 v[10:11], v[2:3], v[26:27]
	v_mov_b32_e32 v2, v40
	v_mov_b32_e32 v3, v8
	v_pk_add_f32 v[2:3], v[2:3], 0 op_sel_hi:[1,0]
	v_mov_b32_e32 v6, v36
	v_mov_b32_e32 v7, v4
	v_pk_add_f32 v[2:3], v[2:3], v[6:7]
	v_mov_b32_e32 v6, v48
	v_mov_b32_e32 v7, v16
	v_pk_add_f32 v[2:3], v[2:3], v[6:7]
	v_mov_b32_e32 v6, v44
	v_mov_b32_e32 v7, v12
	v_pk_add_f32 v[2:3], v[2:3], v[6:7]
	v_mov_b32_e32 v6, v56
	v_mov_b32_e32 v7, v24
	v_pk_add_f32 v[2:3], v[2:3], v[6:7]
	v_mov_b32_e32 v6, v52
	v_mov_b32_e32 v7, v20
	v_pk_add_f32 v[2:3], v[2:3], v[6:7]
	v_mov_b32_e32 v6, v64
	v_mov_b32_e32 v7, v32
	v_pk_add_f32 v[2:3], v[2:3], v[6:7]
	v_mov_b32_e32 v6, v60
	v_mov_b32_e32 v7, v28
	v_mov_b32_e32 v8, v41
	v_pk_add_f32 v[6:7], v[2:3], v[6:7]
	v_pk_add_f32 v[2:3], v[8:9], 0 op_sel_hi:[1,0]
	v_mov_b32_e32 v4, v37
	v_add_u32_e32 v8, s5, v164
	v_pk_add_f32 v[2:3], v[2:3], v[4:5]
	v_mov_b32_e32 v16, v49
	v_ashrrev_i32_e32 v9, 31, v8
	v_pk_add_f32 v[2:3], v[2:3], v[16:17]
	v_mov_b32_e32 v12, v45
	v_lshlrev_b64 v[8:9], 2, v[8:9]
	v_pk_add_f32 v[2:3], v[2:3], v[12:13]
	v_lshl_add_u64 v[12:13], s[86:87], 0, v[8:9]
	v_lshl_add_u64 v[8:9], s[88:89], 0, v[8:9]
	s_waitcnt vmcnt(10)
	v_mov_b32_e32 v5, v204
	v_mov_b32_e32 v92, v58
	v_mov_b32_e32 v8, v205
	v_pk_add_f32 v[90:91], v[90:91], v[92:93]
	s_mov_b32 s14, 0x3b800000
	v_pk_mul_f32 v[12:13], v[90:91], s[14:15] op_sel_hi:[1,0]
	s_add_i32 s2, s4, s7
	v_fma_f32 v9, -v13, v13, v12
	v_max_f32_e32 v9, 0, v9
	v_add_f32_e32 v9, 0x358637bd, v9
	v_cmp_gt_f32_e32 vcc, s33, v9
	v_mul_f32_e32 v12, 0x4b800000, v9
	s_ashr_i32 s3, s2, 31
	v_cndmask_b32_e32 v9, v9, v12, vcc
	v_rsq_f32_e32 v9, v9
	s_lshl_b64 s[2:3], s[2:3], 12
	s_add_u32 s2, s50, s2
	s_addc_u32 s3, s51, s3
	v_mul_f32_e32 v12, 0x45800000, v9
	v_cndmask_b32_e32 v9, v9, v12, vcc
	v_sub_f32_e32 v12, v166, v13
	v_pk_mul_f32 v[10:11], v[10:11], s[14:15] op_sel_hi:[1,0]
	v_mul_f32_e32 v9, v12, v9
	v_lshl_add_u64 v[12:13], v[164:165], 2, s[2:3]
	s_mov_b32 s2, 0x4ec0000
	v_fma_f32 v10, -v11, v11, v10
	v_add_co_u32_e32 v12, vcc, s2, v12
	v_max_f32_e32 v10, 0, v10
	s_nop 0
	v_addc_co_u32_e32 v13, vcc, 0, v13, vcc
	v_add_f32_e32 v10, 0x358637bd, v10
	v_cmp_gt_f32_e32 vcc, s33, v10
	v_mul_f32_e32 v14, 0x4b800000, v10
	v_pk_mul_f32 v[6:7], v[6:7], s[14:15] op_sel_hi:[1,0]
	v_cndmask_b32_e32 v10, v10, v14, vcc
	v_rsq_f32_e32 v10, v10
	v_fma_f32 v6, -v7, v7, v6
	v_sub_f32_e32 v11, v167, v11
	v_max_f32_e32 v6, 0, v6
	v_mul_f32_e32 v14, 0x45800000, v10
	v_cndmask_b32_e32 v10, v10, v14, vcc
	v_mul_f32_e32 v10, v11, v10
	v_add_f32_e32 v6, 0x358637bd, v6
	v_mov_b32_e32 v24, v57
	v_cmp_gt_f32_e32 vcc, s33, v6
	v_pk_add_f32 v[2:3], v[2:3], v[24:25]
	v_mov_b32_e32 v20, v53
	v_pk_add_f32 v[2:3], v[2:3], v[20:21]
	v_mov_b32_e32 v32, v65
	v_pk_add_f32 v[2:3], v[2:3], v[32:33]
	v_mov_b32_e32 v28, v61
	v_pk_add_f32 v[2:3], v[2:3], v[28:29]
	v_sub_f32_e32 v7, v168, v7
	v_pk_mul_f32 v[2:3], v[2:3], s[14:15] op_sel_hi:[1,0]
	v_ashrrev_i32_e32 v4, 6, v164
	v_fma_f32 v2, -v3, v3, v2
	v_max_f32_e32 v2, 0, v2
	v_add_f32_e32 v2, 0x358637bd, v2
	v_sub_f32_e32 v3, v169, v3
	s_movk_i32 s2, 0xd000
	v_fma_f32 v18, v10, v5, v8
	v_mul_f32_e32 v10, 0x4b800000, v6
	v_cndmask_b32_e32 v6, v6, v10, vcc
	v_rsq_f32_e32 v6, v6
	v_fma_f32 v9, v9, v5, v8
	global_store_dword v[12:13], v9, off
	global_store_dword v[12:13], v18, off offset:1024
	v_mul_f32_e32 v10, 0x45800000, v6
	v_cndmask_b32_e32 v6, v6, v10, vcc
	v_mul_f32_e32 v6, v7, v6
	v_fma_f32 v19, v6, v5, v8
	v_cmp_gt_f32_e32 vcc, s33, v2
	v_mul_f32_e32 v6, 0x4b800000, v2
	global_store_dword v[12:13], v19, off offset:2048
	v_cndmask_b32_e32 v2, v2, v6, vcc
	v_rsq_f32_e32 v2, v2
	v_lshlrev_b64 v[10:11], 1, v[164:165]
	v_lshl_add_u64 v[16:17], s[10:11], 0, v[10:11]
	v_mul_f32_e32 v6, 0x45800000, v2
	v_cndmask_b32_e32 v2, v2, v6, vcc
	v_mul_f32_e32 v2, v3, v2
	v_fmac_f32_e32 v8, v2, v5
	v_add_u32_e32 v2, s6, v4
	v_lshlrev_b32_e32 v4, 7, v2
	v_ashrrev_i32_e32 v3, 31, v2
	v_lshlrev_b64 v[2:3], 16, v[2:3]
	v_ashrrev_i32_e32 v5, 31, v4
	global_store_dword v[12:13], v8, off offset:3072
	v_lshl_add_u64 v[14:15], s[90:91], 0, v[2:3]
	v_lshl_add_u64 v[2:3], v[4:5], 2, s[92:93]
	v_mov_b32_e32 v2, v206
	v_mov_b32_e32 v3, v207
	v_mov_b32_e32 v4, v208
	v_mov_b32_e32 v5, v209
	s_nop 0
	v_mov_b32_e32 v6, v210
	v_fma_f32 v2, v9, v6, v2
	v_lshl_add_u64 v[6:7], s[30:31], 0, v[10:11]
	v_add_co_u32_e32 v12, vcc, s2, v6
	v_mov_b32_e32 v10, v212
	v_mov_b32_e32 v11, v213
	s_nop 0
	v_addc_co_u32_e32 v13, vcc, -1, v7, vcc
	v_mov_b32_e32 v12, v220
	s_movk_i32 s2, 0xe000
	v_fma_f32 v10, v9, v10, v3
	v_fmac_f32_e32 v10, v18, v11
	v_lshlrev_b32_e32 v12, 16, v12
	v_mul_f32_e32 v2, v2, v12
	v_bfe_u32 v12, v2, 16, 1
	v_add3_u32 v2, v2, v12, s15
	global_store_short_d16_hi v[240:241], v2, off
	v_add_co_u32_e32 v2, vcc, s2, v6
	s_movk_i32 s2, 0xf000
	s_nop 0
	v_addc_co_u32_e32 v3, vcc, -1, v7, vcc
	v_mov_b32_e32 v2, v221
	v_lshlrev_b32_e32 v2, 16, v2
	v_mul_f32_e32 v2, v10, v2
	v_bfe_u32 v3, v2, 16, 1
	v_add3_u32 v2, v2, v3, s15
	global_store_short_d16_hi v[240:241], v2, off offset:16
	v_mov_b32_e32 v10, v224
	v_mov_b32_e32 v11, v225
	v_mov_b32_e32 v12, v226
	v_add_co_u32_e32 v2, vcc, s2, v6
	s_movk_i32 s2, 0x1000
	s_nop 0
	v_addc_co_u32_e32 v3, vcc, -1, v7, vcc
	v_mov_b32_e32 v2, v222
	v_fma_f32 v4, v9, v10, v4
	v_fmac_f32_e32 v4, v18, v11
	v_fmac_f32_e32 v4, v19, v12
	v_mov_b32_e32 v10, v228
	v_mov_b32_e32 v11, v229
	v_mov_b32_e32 v12, v230
	v_mov_b32_e32 v13, v231
	v_lshlrev_b32_e32 v2, 16, v2
	v_mul_f32_e32 v2, v4, v2
	v_bfe_u32 v3, v2, 16, 1
	v_add3_u32 v4, v2, v3, s15
	v_add_co_u32_e32 v2, vcc, s2, v16
	v_fmac_f32_e32 v5, v9, v10
	v_addc_co_u32_e32 v3, vcc, 0, v17, vcc
	global_store_short_d16_hi v[240:241], v4, off offset:32
	v_mov_b32_e32 v4, v223
	v_fmac_f32_e32 v5, v18, v11
	v_fmac_f32_e32 v5, v19, v12
	v_fmac_f32_e32 v5, v8, v13
	v_lshlrev_b32_e32 v4, 16, v4
	v_mul_f32_e32 v4, v5, v4
	v_bfe_u32 v5, v4, 16, 1
	v_add3_u32 v4, v4, v5, s15
	global_store_short_d16_hi v[240:241], v4, off offset:48
	s_branch .LBB0_782

.LBB0_859:
	s_or_b64 exec, exec, s[2:3]
	v_readlane_b32 s2, v242, 9
	s_waitcnt lgkmcnt(0)
	s_barrier
	v_mov_b32_e32 v2, s2
	v_readlane_b32 s2, v242, 10
	s_nop 1
	v_mov_b32_e32 v3, s2
	v_readlane_b32 s2, v242, 11
	ds_read_b128 v[6:9], v2
	ds_read_b128 v[2:5], v3
	v_mov_b32_e32 v10, s2
	v_readlane_b32 s2, v242, 12
	s_nop 1
	v_mov_b32_e32 v11, s2
	v_readlane_b32 s2, v242, 13
	ds_read_b128 v[14:17], v10
	ds_read_b128 v[10:13], v11
	v_mov_b32_e32 v18, s2
	v_readlane_b32 s2, v242, 14
	s_nop 1
	v_mov_b32_e32 v19, s2
	v_readlane_b32 s2, v242, 15
	ds_read_b128 v[22:25], v18
	ds_read_b128 v[18:21], v19
	v_mov_b32_e32 v26, s2
	v_readlane_b32 s2, v242, 16
	s_nop 1
	v_mov_b32_e32 v27, s2
	v_readlane_b32 s2, v242, 17
	ds_read_b128 v[30:33], v26
	ds_read_b128 v[26:29], v27
	v_mov_b32_e32 v34, s2
	v_readlane_b32 s2, v242, 18
	s_nop 1
	v_mov_b32_e32 v35, s2
	v_readlane_b32 s2, v242, 19
	ds_read_b128 v[38:41], v34
	ds_read_b128 v[34:37], v35
	v_mov_b32_e32 v42, s2
	v_readlane_b32 s2, v242, 20
	s_nop 1
	v_mov_b32_e32 v43, s2
	v_readlane_b32 s2, v242, 21
	ds_read_b128 v[46:49], v42
	ds_read_b128 v[42:45], v43
	v_mov_b32_e32 v50, s2
	v_readlane_b32 s2, v242, 22
	s_nop 1
	v_mov_b32_e32 v51, s2
	v_readlane_b32 s2, v242, 23
	ds_read_b128 v[54:57], v50
	ds_read_b128 v[50:53], v51
	v_mov_b32_e32 v58, s2
	v_readlane_b32 s2, v242, 24
	s_nop 1
	v_mov_b32_e32 v59, s2
	ds_read_b128 v[62:65], v58
	ds_read_b128 v[58:61], v59
	s_and_saveexec_b64 s[34:35], s[38:39]
	s_cbranch_execz .LBB0_861
	v_lshlrev_b64 v[142:143], 2, v[138:139]
	v_lshl_add_u64 v[144:145], s[80:81], 0, v[142:143]
	v_lshl_add_u64 v[142:143], s[82:83], 0, v[142:143]
	global_load_dword v164, v[144:145], off
	global_load_dword v154, v[142:143], off
	v_readlane_b32 s2, v242, 25
	s_mov_b32 s12, 0x3b2aaaab
	s_nop 0
	v_mov_b32_e32 v66, s2
	v_readlane_b32 s2, v242, 26
	ds_read_b128 v[66:69], v66
	s_nop 0
	v_mov_b32_e32 v70, s2
	v_readlane_b32 s2, v242, 27
	ds_read_b128 v[70:73], v70
	s_waitcnt lgkmcnt(0)
	v_mov_b32_e32 v142, v70
	v_mov_b32_e32 v74, s2
	v_readlane_b32 s2, v242, 28
	ds_read_b128 v[74:77], v74
	s_nop 0
	v_mov_b32_e32 v78, s2
	v_readlane_b32 s2, v242, 29
	ds_read_b128 v[78:81], v78
	s_nop 0
	v_mov_b32_e32 v82, s2
	v_readlane_b32 s2, v242, 30
	ds_read_b128 v[82:85], v82
	s_nop 0
	v_mov_b32_e32 v86, s2
	v_readlane_b32 s2, v242, 31
	ds_read_b128 v[86:89], v86
	s_nop 0
	v_mov_b32_e32 v90, s2
	v_readlane_b32 s2, v242, 32
	ds_read_b128 v[90:93], v90
	s_nop 0
	v_mov_b32_e32 v94, s2
	s_add_i32 s2, 32, 0x16000
	v_mov_b32_e32 v98, s2
	v_readlane_b32 s2, v242, 33
	ds_read_b128 v[98:101], v98
	ds_read_b128 v[94:97], v94
	v_mov_b32_e32 v102, s2
	v_readlane_b32 s2, v242, 34
	ds_read_b128 v[102:105], v102
	s_waitcnt lgkmcnt(0)
	v_mov_b32_e32 v143, v102
	v_mov_b32_e32 v106, s2
	v_readlane_b32 s2, v242, 35
	ds_read_b128 v[106:109], v106
	v_mov_b32_e32 v102, v71
	v_mov_b32_e32 v110, s2
	v_readlane_b32 s2, v242, 36
	ds_read_b128 v[110:113], v110
	s_nop 0
	v_mov_b32_e32 v114, s2
	v_readlane_b32 s2, v242, 37
	ds_read_b128 v[114:117], v114
	s_nop 0
	v_mov_b32_e32 v118, s2
	v_readlane_b32 s2, v242, 38
	ds_read_b128 v[118:121], v118
	s_nop 0
	v_mov_b32_e32 v122, s2
	v_readlane_b32 s2, v242, 39
	ds_read_b128 v[122:125], v122
	s_nop 0
	v_mov_b32_e32 v126, s2
	v_readlane_b32 s2, v242, 40
	s_mulk_i32 s2, 0x300
	ds_read_b128 v[126:129], v126
	v_add_u32_e32 v138, s2, v138
	v_ashrrev_i32_e32 v139, 31, v138
	v_lshl_add_u64 v[138:139], v[138:139], 2, s[84:85]
	global_load_dword v151, v[138:139], off
	global_load_dword v153, v[138:139], off offset:1536
	global_load_dword v152, v[138:139], off offset:3072
	v_mov_b32_e32 v138, v66
	v_mov_b32_e32 v139, v98
	v_pk_add_f32 v[138:139], v[138:139], 0 op_sel_hi:[1,0]
	s_movk_i32 s2, 0xd000
	v_pk_add_f32 v[138:139], v[138:139], v[142:143]
	v_mov_b32_e32 v142, v74
	s_waitcnt lgkmcnt(5)
	v_mov_b32_e32 v143, v106
	v_pk_add_f32 v[138:139], v[138:139], v[142:143]
	v_mov_b32_e32 v142, v78
	s_waitcnt lgkmcnt(4)
	v_mov_b32_e32 v143, v110
	v_pk_add_f32 v[138:139], v[138:139], v[142:143]
	v_mov_b32_e32 v142, v82
	s_waitcnt lgkmcnt(3)
	v_mov_b32_e32 v143, v114
	v_pk_add_f32 v[138:139], v[138:139], v[142:143]
	v_mov_b32_e32 v142, v86
	s_waitcnt lgkmcnt(2)
	v_mov_b32_e32 v143, v118
	v_pk_add_f32 v[138:139], v[138:139], v[142:143]
	v_mov_b32_e32 v142, v90
	s_waitcnt lgkmcnt(1)
	v_mov_b32_e32 v143, v122
	v_pk_add_f32 v[138:139], v[138:139], v[142:143]
	v_mov_b32_e32 v142, v94
	s_waitcnt lgkmcnt(0)
	v_mov_b32_e32 v143, v126
	v_pk_add_f32 v[138:139], v[138:139], v[142:143]
	v_lshlrev_b64 v[142:143], 1, v[130:131]
	v_pk_mul_f32 v[138:139], v[138:139], s[12:13] op_sel_hi:[1,0]
	v_mov_b32_e32 v98, v67
	v_fma_f32 v66, -v139, v139, v138
	v_max_f32_e32 v66, 0, v66
	v_add_f32_e32 v66, 0x358637bd, v66
	v_cmp_gt_f32_e32 vcc, s33, v66
	v_mul_f32_e32 v70, 0x4b800000, v66
	v_mov_b32_e32 v106, v75
	v_cndmask_b32_e32 v66, v66, v70, vcc
	v_rsq_f32_e32 v66, v66
	v_mov_b32_e32 v110, v79
	v_mov_b32_e32 v114, v83
	v_mov_b32_e32 v118, v87
	v_mul_f32_e32 v70, 0x45800000, v66
	v_cndmask_b32_e32 v66, v66, v70, vcc
	v_sub_f32_e32 v70, v140, v139
	v_mul_f32_e32 v66, v70, v66
	s_waitcnt vmcnt(3)
	v_fma_f32 v66, v164, v66, v154
	v_mul_f32_e32 v70, 0xbfb8aa3b, v66
	v_exp_f32_e32 v70, v70
	v_lshl_add_u64 v[138:139], s[30:31], 0, v[142:143]
	v_add_co_u32_e32 v144, vcc, s2, v138
	v_add_f32_e32 v70, 1.0, v70
	v_rcp_f32_e32 v70, v70
	v_addc_co_u32_e32 v145, vcc, -1, v139, vcc
	v_lshl_add_u64 v[142:143], s[10:11], 0, v[142:143]
	v_mul_f32_e32 v66, v66, v70
	v_mov_b32_e32 v122, v91
	v_mov_b32_e32 v126, v95
	s_movk_i32 s2, 0xe000
	s_waitcnt vmcnt(0)
	v_lshlrev_b32_e32 v70, 16, v192
	v_mul_f32_e32 v66, v66, v70
	v_bfe_u32 v70, v66, 16, 1
	v_add3_u32 v66, v66, v70, s15
	v_lshrrev_b32_e64 v245, 3, s7
	v_lshlrev_b32_e32 v245, 16, v245
	v_and_b32_e64 v246, s7, 7
	v_lshl_add_u32 v245, v246, 6, v245
	v_add_u32_e32 v245, 0x2000000, v245
	v_mov_b32_e32 v247, 0
	v_mov_b32_e32 v252, v0
	v_lshrrev_b32_e32 v246, 7, v252
	v_lshl_add_u32 v246, v246, 13, v245
	v_bfe_u32 v253, v252, 4, 3
	v_lshl_add_u32 v246, v253, 10, v246
	v_bfe_u32 v253, v252, 3, 1
	v_lshl_add_u32 v246, v253, 9, v246
	v_and_b32_e32 v253, 7, v252
	v_lshl_add_u32 v246, v253, 1, v246
	v_lshl_add_u64 v[236:237], s[62:63], 0, v[246:247]
	v_add_u32_e32 v252, 0x180, v0
	v_lshrrev_b32_e32 v246, 7, v252
	v_lshl_add_u32 v246, v246, 13, v245
	v_bfe_u32 v253, v252, 4, 3
	v_lshl_add_u32 v246, v253, 10, v246
	v_bfe_u32 v253, v252, 3, 1
	v_lshl_add_u32 v246, v253, 9, v246
	v_and_b32_e32 v253, 7, v252
	v_lshl_add_u32 v246, v253, 1, v246
	v_lshl_add_u64 v[238:239], s[62:63], 0, v[246:247]
	v_add_u32_e32 v252, 0x300, v0
	v_lshrrev_b32_e32 v246, 7, v252
	v_lshl_add_u32 v246, v246, 13, v245
	v_bfe_u32 v253, v252, 4, 3
	v_lshl_add_u32 v246, v253, 10, v246
	v_bfe_u32 v253, v252, 3, 1
	v_lshl_add_u32 v246, v253, 9, v246
	v_and_b32_e32 v253, 7, v252
	v_lshl_add_u32 v246, v253, 1, v246
	v_lshl_add_u64 v[240:241], s[62:63], 0, v[246:247]
	global_store_short_d16_hi v[236:237], v66, off
	v_mul_f32_e32 v66, v150, v153
	v_fmac_f32_e32 v66, v165, v151
	v_fmac_f32_e32 v66, v149, v152
	v_lshlrev_b32_e32 v70, 16, v193
	v_mul_f32_e32 v66, v66, v70
	v_bfe_u32 v70, v66, 16, 1
	v_add3_u32 v66, v66, v70, s15
	global_store_short_d16_hi v[238:239], v66, off
	v_pk_add_f32 v[66:67], v[98:99], 0 op_sel_hi:[1,0]
	s_nop 0
	v_pk_add_f32 v[66:67], v[66:67], v[102:103]
	s_nop 0
	v_pk_add_f32 v[66:67], v[66:67], v[106:107]
	s_nop 0
	v_pk_add_f32 v[66:67], v[66:67], v[110:111]
	s_nop 0
	v_pk_add_f32 v[66:67], v[66:67], v[114:115]
	s_nop 0
	v_pk_add_f32 v[66:67], v[66:67], v[118:119]
	s_nop 0
	v_pk_add_f32 v[66:67], v[66:67], v[122:123]
	s_nop 0
	v_pk_add_f32 v[66:67], v[66:67], v[126:127]
	s_nop 0
	v_pk_mul_f32 v[66:67], v[66:67], s[12:13] op_sel_hi:[1,0]
	s_nop 0
	v_fma_f32 v66, -v67, v67, v66
	v_max_f32_e32 v66, 0, v66
	v_add_f32_e32 v66, 0x358637bd, v66
	v_cmp_gt_f32_e32 vcc, s33, v66
	v_mul_f32_e32 v70, 0x4b800000, v66
	v_sub_f32_e32 v67, v141, v67
	v_cndmask_b32_e32 v66, v66, v70, vcc
	v_rsq_f32_e32 v66, v66
	s_nop 0
	v_mul_f32_e32 v70, 0x45800000, v66
	v_cndmask_b32_e32 v66, v66, v70, vcc
	v_mul_f32_e32 v66, v67, v66
	v_fma_f32 v66, v164, v66, v154
	v_mul_f32_e32 v67, 0xbfb8aa3b, v66
	v_exp_f32_e32 v67, v67
	s_nop 0
	v_add_f32_e32 v67, 1.0, v67
	v_rcp_f32_e32 v67, v67
	s_nop 0
	v_mul_f32_e32 v70, v66, v67
	v_add_co_u32_e32 v66, vcc, s2, v138
	s_movk_i32 s2, 0xf000
	s_nop 0
	v_addc_co_u32_e32 v67, vcc, -1, v139, vcc
	v_lshlrev_b32_e32 v71, 16, v194
	v_mul_f32_e32 v70, v70, v71
	v_bfe_u32 v71, v70, 16, 1
	v_add3_u32 v70, v70, v71, s15
	global_store_short_d16_hi v[236:237], v70, off offset:16
	v_mul_f32_e32 v70, v149, v153
	v_fmac_f32_e32 v70, v150, v151
	v_fmac_f32_e32 v70, v148, v152
	v_mov_b32_e32 v71, v104
	v_mov_b32_e32 v104, v73
	v_lshlrev_b32_e32 v66, 16, v195
	v_mul_f32_e32 v66, v70, v66
	v_bfe_u32 v67, v66, 16, 1
	v_add3_u32 v66, v66, v67, s15
	global_store_short_d16_hi v[238:239], v66, off offset:16
	v_mov_b32_e32 v66, v68
	v_mov_b32_e32 v67, v100
	v_pk_add_f32 v[66:67], v[66:67], 0 op_sel_hi:[1,0]
	v_mov_b32_e32 v70, v72
	v_pk_add_f32 v[66:67], v[66:67], v[70:71]
	v_mov_b32_e32 v70, v76
	v_mov_b32_e32 v71, v108
	v_pk_add_f32 v[66:67], v[66:67], v[70:71]
	v_mov_b32_e32 v70, v80
	v_mov_b32_e32 v71, v112
	v_pk_add_f32 v[66:67], v[66:67], v[70:71]
	v_mov_b32_e32 v70, v84
	v_mov_b32_e32 v71, v116
	v_pk_add_f32 v[66:67], v[66:67], v[70:71]
	v_mov_b32_e32 v70, v88
	v_mov_b32_e32 v71, v120
	v_pk_add_f32 v[66:67], v[66:67], v[70:71]
	v_mov_b32_e32 v70, v92
	v_mov_b32_e32 v71, v124
	v_pk_add_f32 v[66:67], v[66:67], v[70:71]
	v_mov_b32_e32 v70, v96
	v_mov_b32_e32 v71, v128
	v_pk_add_f32 v[66:67], v[66:67], v[70:71]
	v_mov_b32_e32 v100, v69
	v_pk_mul_f32 v[66:67], v[66:67], s[12:13] op_sel_hi:[1,0]
	v_mov_b32_e32 v108, v77
	v_fma_f32 v66, -v67, v67, v66
	v_max_f32_e32 v66, 0, v66
	v_add_f32_e32 v66, 0x358637bd, v66
	v_cmp_gt_f32_e32 vcc, s33, v66
	v_mul_f32_e32 v68, 0x4b800000, v66
	v_sub_f32_e32 v67, v136, v67
	v_cndmask_b32_e32 v66, v66, v68, vcc
	v_rsq_f32_e32 v66, v66
	v_mov_b32_e32 v112, v81
	v_mov_b32_e32 v116, v85
	v_mov_b32_e32 v120, v89
	v_mul_f32_e32 v68, 0x45800000, v66
	v_cndmask_b32_e32 v66, v66, v68, vcc
	v_mul_f32_e32 v66, v67, v66
	v_fma_f32 v66, v66, v164, v154
	v_mul_f32_e32 v67, 0xbfb8aa3b, v66
	v_exp_f32_e32 v67, v67
	v_add_co_u32_e32 v70, vcc, s2, v138
	s_movk_i32 s2, 0x1000
	v_add_f32_e32 v67, 1.0, v67
	v_rcp_f32_e32 v67, v67
	v_addc_co_u32_e32 v71, vcc, -1, v139, vcc
	v_mov_b32_e32 v124, v93
	v_mul_f32_e32 v66, v66, v67
	v_mov_b32_e32 v128, v97
	v_lshlrev_b32_e32 v67, 16, v196
	v_mul_f32_e32 v66, v66, v67
	v_bfe_u32 v67, v66, 16, 1
	v_add3_u32 v68, v66, v67, s15
	v_add_co_u32_e32 v66, vcc, s2, v142
	s_add_i32 s2, s4, s7
	s_nop 0
	v_addc_co_u32_e32 v67, vcc, 0, v143, vcc
	global_store_short_d16_hi v[236:237], v68, off offset:32
	v_mul_f32_e32 v68, v148, v153
	v_fmac_f32_e32 v68, v149, v151
	v_fmac_f32_e32 v68, v147, v152
	s_mul_hi_i32 s3, s2, 0xc00
	s_mulk_i32 s2, 0xc00
	s_add_u32 s2, s50, s2
	s_addc_u32 s3, s51, s3
	v_lshlrev_b32_e32 v70, 16, v197
	v_mul_f32_e32 v68, v68, v70
	v_bfe_u32 v70, v68, 16, 1
	v_add3_u32 v68, v68, v70, s15
	global_store_short_d16_hi v[238:239], v68, off offset:32
	v_pk_add_f32 v[68:69], v[100:101], 0 op_sel_hi:[1,0]
	s_nop 0
	v_pk_add_f32 v[68:69], v[68:69], v[104:105]
	s_nop 0
	v_pk_add_f32 v[68:69], v[68:69], v[108:109]
	s_nop 0
	v_pk_add_f32 v[68:69], v[68:69], v[112:113]
	s_nop 0
	v_pk_add_f32 v[68:69], v[68:69], v[116:117]
	s_nop 0
	v_pk_add_f32 v[68:69], v[68:69], v[120:121]
	s_nop 0
	v_pk_add_f32 v[68:69], v[68:69], v[124:125]
	s_nop 0
	v_pk_add_f32 v[68:69], v[68:69], v[128:129]
	s_nop 0
	v_pk_mul_f32 v[68:69], v[68:69], s[12:13] op_sel_hi:[1,0]
	s_nop 0
	v_fma_f32 v68, -v69, v69, v68
	v_max_f32_e32 v68, 0, v68
	v_add_f32_e32 v68, 0x358637bd, v68
	v_cmp_gt_f32_e32 vcc, s33, v68
	v_mul_f32_e32 v70, 0x4b800000, v68
	v_sub_f32_e32 v69, v137, v69
	v_cndmask_b32_e32 v68, v68, v70, vcc
	v_rsq_f32_e32 v68, v68
	s_nop 0
	v_mul_f32_e32 v70, 0x45800000, v68
	v_cndmask_b32_e32 v68, v68, v70, vcc
	v_mul_f32_e32 v68, v69, v68
	v_fmac_f32_e32 v154, v68, v164
	v_mul_f32_e32 v68, 0xbfb8aa3b, v154
	v_exp_f32_e32 v68, v68
	v_lshlrev_b32_e32 v69, 16, v198
	v_add_f32_e32 v68, 1.0, v68
	v_rcp_f32_e32 v68, v68
	s_nop 0
	v_mul_f32_e32 v68, v154, v68
	v_mul_f32_e32 v68, v68, v69
	v_bfe_u32 v69, v68, 16, 1
	v_add3_u32 v68, v68, v69, s15
	global_store_short_d16_hi v[236:237], v68, off offset:48
	v_mul_f32_e32 v68, v147, v153
	v_fmac_f32_e32 v68, v148, v151
	v_fmac_f32_e32 v68, v146, v152
	v_lshlrev_b32_e32 v69, 16, v199
	v_mul_f32_e32 v68, v68, v69
	v_bfe_u32 v69, v68, 16, 1
	v_add3_u32 v68, v68, v69, s15
	global_store_short_d16_hi v[238:239], v68, off offset:48
	v_lshl_add_u64 v[66:67], v[130:131], 2, s[2:3]
	v_add_co_u32_e32 v66, vcc, 0x4e00000, v66
	s_nop 1
	v_addc_co_u32_e32 v67, vcc, 0, v67, vcc
	global_store_dword v[66:67], v147, off
	global_store_dword v[66:67], v146, off offset:1536
.LBB0_861:
	s_or_b64 exec, exec, s[34:35]
	s_and_saveexec_b64 s[12:13], s[36:37]
	s_cbranch_execz .LBB0_852
	s_waitcnt lgkmcnt(7)
	v_mov_b32_e32 v66, v38
	v_mov_b32_e32 v67, v6
	v_mov_b32_e32 v6, v39
	v_pk_add_f32 v[66:67], v[66:67], 0 op_sel_hi:[1,0]
	s_waitcnt lgkmcnt(6)
	v_mov_b32_e32 v68, v34
	v_mov_b32_e32 v69, v2
	v_pk_add_f32 v[6:7], v[6:7], 0 op_sel_hi:[1,0]
	v_mov_b32_e32 v2, v35
	v_pk_add_f32 v[66:67], v[66:67], v[68:69]
	s_waitcnt lgkmcnt(5)
	v_mov_b32_e32 v68, v46
	v_mov_b32_e32 v69, v14
	v_pk_add_f32 v[2:3], v[6:7], v[2:3]
	v_mov_b32_e32 v14, v47
	v_pk_add_f32 v[66:67], v[66:67], v[68:69]
	s_waitcnt lgkmcnt(4)
	v_mov_b32_e32 v68, v42
	v_mov_b32_e32 v69, v10
	v_pk_add_f32 v[2:3], v[2:3], v[14:15]
	v_mov_b32_e32 v10, v43
	v_pk_add_f32 v[66:67], v[66:67], v[68:69]
	s_waitcnt lgkmcnt(3)
	v_mov_b32_e32 v68, v54
	v_mov_b32_e32 v69, v22
	v_pk_add_f32 v[2:3], v[2:3], v[10:11]
	v_mov_b32_e32 v22, v55
	v_pk_add_f32 v[66:67], v[66:67], v[68:69]
	s_waitcnt lgkmcnt(2)
	v_mov_b32_e32 v68, v50
	v_mov_b32_e32 v69, v18
	v_pk_add_f32 v[2:3], v[2:3], v[22:23]
	v_mov_b32_e32 v18, v51
	v_pk_add_f32 v[66:67], v[66:67], v[68:69]
	s_waitcnt lgkmcnt(1)
	v_mov_b32_e32 v68, v62
	v_mov_b32_e32 v69, v30
	v_pk_add_f32 v[2:3], v[2:3], v[18:19]
	v_mov_b32_e32 v30, v63
	v_pk_add_f32 v[66:67], v[66:67], v[68:69]
	v_mov_b32_e32 v69, v26
	v_pk_add_f32 v[2:3], v[2:3], v[30:31]
	s_waitcnt lgkmcnt(0)
	v_mov_b32_e32 v26, v59
	v_pk_add_f32 v[10:11], v[2:3], v[26:27]
	v_mov_b32_e32 v2, v40
	v_mov_b32_e32 v3, v8
	v_pk_add_f32 v[2:3], v[2:3], 0 op_sel_hi:[1,0]
	v_mov_b32_e32 v6, v36
	v_mov_b32_e32 v7, v4
	v_pk_add_f32 v[2:3], v[2:3], v[6:7]
	v_mov_b32_e32 v6, v48
	v_mov_b32_e32 v7, v16
	v_pk_add_f32 v[2:3], v[2:3], v[6:7]
	v_mov_b32_e32 v6, v44
	v_mov_b32_e32 v7, v12
	v_pk_add_f32 v[2:3], v[2:3], v[6:7]
	v_mov_b32_e32 v6, v56
	v_mov_b32_e32 v7, v24
	v_pk_add_f32 v[2:3], v[2:3], v[6:7]
	v_mov_b32_e32 v6, v52
	v_mov_b32_e32 v7, v20
	v_pk_add_f32 v[2:3], v[2:3], v[6:7]
	v_mov_b32_e32 v6, v64
	v_mov_b32_e32 v7, v32
	v_pk_add_f32 v[2:3], v[2:3], v[6:7]
	v_mov_b32_e32 v6, v60
	v_mov_b32_e32 v7, v28
	v_mov_b32_e32 v8, v41
	v_pk_add_f32 v[6:7], v[2:3], v[6:7]
	v_pk_add_f32 v[2:3], v[8:9], 0 op_sel_hi:[1,0]
	v_mov_b32_e32 v4, v37
	v_add_u32_e32 v8, s5, v130
	v_pk_add_f32 v[2:3], v[2:3], v[4:5]
	v_mov_b32_e32 v16, v49
	v_ashrrev_i32_e32 v9, 31, v8
	v_pk_add_f32 v[2:3], v[2:3], v[16:17]
	v_mov_b32_e32 v12, v45
	v_lshlrev_b64 v[8:9], 2, v[8:9]
	v_pk_add_f32 v[2:3], v[2:3], v[12:13]
	v_lshl_add_u64 v[12:13], s[86:87], 0, v[8:9]
	v_lshl_add_u64 v[8:9], s[88:89], 0, v[8:9]
	s_waitcnt vmcnt(10)
	v_mov_b32_e32 v5, v204
	v_mov_b32_e32 v68, v58
	v_mov_b32_e32 v8, v205
	v_pk_add_f32 v[66:67], v[66:67], v[68:69]
	s_mov_b32 s14, 0x3b800000
	v_pk_mul_f32 v[12:13], v[66:67], s[14:15] op_sel_hi:[1,0]
	s_add_i32 s2, s4, s7
	v_fma_f32 v9, -v13, v13, v12
	v_max_f32_e32 v9, 0, v9
	v_add_f32_e32 v9, 0x358637bd, v9
	v_cmp_gt_f32_e32 vcc, s33, v9
	v_mul_f32_e32 v12, 0x4b800000, v9
	s_ashr_i32 s3, s2, 31
	v_cndmask_b32_e32 v9, v9, v12, vcc
	v_rsq_f32_e32 v9, v9
	s_lshl_b64 s[2:3], s[2:3], 12
	s_add_u32 s2, s50, s2
	s_addc_u32 s3, s51, s3
	v_mul_f32_e32 v12, 0x45800000, v9
	v_cndmask_b32_e32 v9, v9, v12, vcc
	v_sub_f32_e32 v12, v132, v13
	v_pk_mul_f32 v[10:11], v[10:11], s[14:15] op_sel_hi:[1,0]
	v_mul_f32_e32 v9, v12, v9
	v_lshl_add_u64 v[12:13], v[130:131], 2, s[2:3]
	s_mov_b32 s2, 0x4ec0000
	v_fma_f32 v10, -v11, v11, v10
	v_add_co_u32_e32 v12, vcc, s2, v12
	v_max_f32_e32 v10, 0, v10
	s_nop 0
	v_addc_co_u32_e32 v13, vcc, 0, v13, vcc
	v_add_f32_e32 v10, 0x358637bd, v10
	v_cmp_gt_f32_e32 vcc, s33, v10
	v_mul_f32_e32 v14, 0x4b800000, v10
	v_pk_mul_f32 v[6:7], v[6:7], s[14:15] op_sel_hi:[1,0]
	v_cndmask_b32_e32 v10, v10, v14, vcc
	v_rsq_f32_e32 v10, v10
	v_fma_f32 v6, -v7, v7, v6
	v_sub_f32_e32 v11, v133, v11
	v_max_f32_e32 v6, 0, v6
	v_mul_f32_e32 v14, 0x45800000, v10
	v_cndmask_b32_e32 v10, v10, v14, vcc
	v_mul_f32_e32 v10, v11, v10
	v_add_f32_e32 v6, 0x358637bd, v6
	v_mov_b32_e32 v24, v57
	v_cmp_gt_f32_e32 vcc, s33, v6
	v_pk_add_f32 v[2:3], v[2:3], v[24:25]
	v_mov_b32_e32 v20, v53
	v_pk_add_f32 v[2:3], v[2:3], v[20:21]
	v_mov_b32_e32 v32, v65
	v_pk_add_f32 v[2:3], v[2:3], v[32:33]
	v_mov_b32_e32 v28, v61
	v_pk_add_f32 v[2:3], v[2:3], v[28:29]
	v_sub_f32_e32 v7, v134, v7
	v_pk_mul_f32 v[2:3], v[2:3], s[14:15] op_sel_hi:[1,0]
	v_ashrrev_i32_e32 v4, 6, v130
	v_fma_f32 v2, -v3, v3, v2
	v_max_f32_e32 v2, 0, v2
	v_add_f32_e32 v2, 0x358637bd, v2
	v_sub_f32_e32 v3, v135, v3
	s_movk_i32 s2, 0xd000
	v_fma_f32 v18, v10, v5, v8
	v_mul_f32_e32 v10, 0x4b800000, v6
	v_cndmask_b32_e32 v6, v6, v10, vcc
	v_rsq_f32_e32 v6, v6
	v_fma_f32 v9, v9, v5, v8
	global_store_dword v[12:13], v9, off
	global_store_dword v[12:13], v18, off offset:1024
	v_mul_f32_e32 v10, 0x45800000, v6
	v_cndmask_b32_e32 v6, v6, v10, vcc
	v_mul_f32_e32 v6, v7, v6
	v_fma_f32 v19, v6, v5, v8
	v_cmp_gt_f32_e32 vcc, s33, v2
	v_mul_f32_e32 v6, 0x4b800000, v2
	global_store_dword v[12:13], v19, off offset:2048
	v_cndmask_b32_e32 v2, v2, v6, vcc
	v_rsq_f32_e32 v2, v2
	v_lshlrev_b64 v[10:11], 1, v[130:131]
	v_lshl_add_u64 v[16:17], s[10:11], 0, v[10:11]
	v_mul_f32_e32 v6, 0x45800000, v2
	v_cndmask_b32_e32 v2, v2, v6, vcc
	v_mul_f32_e32 v2, v3, v2
	v_fmac_f32_e32 v8, v2, v5
	v_add_u32_e32 v2, s6, v4
	v_lshlrev_b32_e32 v4, 7, v2
	v_ashrrev_i32_e32 v3, 31, v2
	v_lshlrev_b64 v[2:3], 16, v[2:3]
	v_ashrrev_i32_e32 v5, 31, v4
	global_store_dword v[12:13], v8, off offset:3072
	v_lshl_add_u64 v[14:15], s[90:91], 0, v[2:3]
	v_lshl_add_u64 v[2:3], v[4:5], 2, s[92:93]
	v_mov_b32_e32 v2, v206
	v_mov_b32_e32 v3, v207
	v_mov_b32_e32 v4, v208
	v_mov_b32_e32 v5, v209
	s_nop 0
	v_mov_b32_e32 v6, v210
	v_fma_f32 v2, v9, v6, v2
	v_lshl_add_u64 v[6:7], s[30:31], 0, v[10:11]
	v_add_co_u32_e32 v12, vcc, s2, v6
	v_mov_b32_e32 v10, v212
	v_mov_b32_e32 v11, v213
	s_nop 0
	v_addc_co_u32_e32 v13, vcc, -1, v7, vcc
	v_mov_b32_e32 v12, v220
	s_movk_i32 s2, 0xe000
	v_fma_f32 v10, v9, v10, v3
	v_fmac_f32_e32 v10, v18, v11
	v_lshlrev_b32_e32 v12, 16, v12
	v_mul_f32_e32 v2, v2, v12
	v_bfe_u32 v12, v2, 16, 1
	v_add3_u32 v2, v2, v12, s15
	global_store_short_d16_hi v[240:241], v2, off
	v_add_co_u32_e32 v2, vcc, s2, v6
	s_movk_i32 s2, 0xf000
	s_nop 0
	v_addc_co_u32_e32 v3, vcc, -1, v7, vcc
	v_mov_b32_e32 v2, v221
	v_lshlrev_b32_e32 v2, 16, v2
	v_mul_f32_e32 v2, v10, v2
	v_bfe_u32 v3, v2, 16, 1
	v_add3_u32 v2, v2, v3, s15
	global_store_short_d16_hi v[240:241], v2, off offset:16
	v_mov_b32_e32 v10, v224
	v_mov_b32_e32 v11, v225
	v_mov_b32_e32 v12, v226
	v_add_co_u32_e32 v2, vcc, s2, v6
	s_movk_i32 s2, 0x1000
	s_nop 0
	v_addc_co_u32_e32 v3, vcc, -1, v7, vcc
	v_mov_b32_e32 v2, v222
	v_fma_f32 v4, v9, v10, v4
	v_fmac_f32_e32 v4, v18, v11
	v_fmac_f32_e32 v4, v19, v12
	v_mov_b32_e32 v10, v228
	v_mov_b32_e32 v11, v229
	v_mov_b32_e32 v12, v230
	v_mov_b32_e32 v13, v231
	v_lshlrev_b32_e32 v2, 16, v2
	v_mul_f32_e32 v2, v4, v2
	v_bfe_u32 v3, v2, 16, 1
	v_add3_u32 v4, v2, v3, s15
	v_add_co_u32_e32 v2, vcc, s2, v16
	v_fmac_f32_e32 v5, v9, v10
	v_addc_co_u32_e32 v3, vcc, 0, v17, vcc
	global_store_short_d16_hi v[240:241], v4, off offset:32
	v_mov_b32_e32 v4, v223
	v_fmac_f32_e32 v5, v18, v11
	v_fmac_f32_e32 v5, v19, v12
	v_fmac_f32_e32 v5, v8, v13
	v_lshlrev_b32_e32 v4, 16, v4
	v_mul_f32_e32 v4, v5, v4
	v_bfe_u32 v5, v4, 16, 1
	v_add3_u32 v4, v4, v5, s15
	global_store_short_d16_hi v[240:241], v4, off offset:48
	s_branch .LBB0_852

.LBB0_921:
	s_and_b32 s3, s5, 0x3c0
	v_or_b32_e32 v2, s3, v43
	v_lshlrev_b32_e32 v154, 11, v2
	s_and_b32 s2, s4, 0xffffffe0
	v_lshl_add_u64 v[60:61], v[38:39], 0, v[154:155]
	v_add_u32_e32 v40, s2, v42
	v_ashrrev_i32_e32 v41, 31, v40
	v_lshlrev_b64 v[62:63], 11, v[40:41]
	v_lshl_add_u64 v[64:65], v[36:37], 0, v[62:63]
	s_mov_b32 s2, 0x10000
	v_add_co_u32_e32 v66, vcc, s2, v60
	s_mov_b32 s2, 0x7060302
	s_nop 0
	v_addc_co_u32_e32 v67, vcc, 0, v61, vcc
	v_lshrrev_b32_e64 v64, 4, s6
	v_lshrrev_b32_e32 v65, 6, v0
	v_lshl_add_u32 v64, v64, 3, v65
	v_lshlrev_b32_e32 v64, 13, v64
	v_and_b32_e32 v65, 63, v0
	v_lshl_add_u32 v64, v65, 4, v64
	v_add_u32_e32 v64, 0x2001000, v64
	v_mov_b32_e32 v65, 0
	v_lshl_add_u64 v[64:65], s[62:63], 0, v[64:65]
	global_load_dwordx4 v[68:71], v[60:61], off
	global_load_dwordx4 v[100:103], v[64:65], off offset:-4096
	global_load_dwordx4 v[182:185], v[66:67], off
	global_load_dwordx4 v[72:75], v[60:61], off offset:32
	global_load_dwordx4 v[104:107], v[64:65], off offset:-3072
	global_load_dwordx4 v[186:189], v[66:67], off offset:32
	global_load_dwordx4 v[76:79], v[60:61], off offset:64
	global_load_dwordx4 v[108:111], v[64:65], off offset:-2048
	global_load_dwordx4 v[190:193], v[66:67], off offset:64
	global_load_dwordx4 v[80:83], v[60:61], off offset:96
	global_load_dwordx4 v[112:115], v[64:65], off offset:-1024
	global_load_dwordx4 v[194:197], v[66:67], off offset:96
	global_load_dwordx4 v[84:87], v[60:61], off offset:128
	global_load_dwordx4 v[116:119], v[64:65], off
	global_load_dwordx4 v[198:201], v[66:67], off offset:128
	global_load_dwordx4 v[88:91], v[60:61], off offset:160
	global_load_dwordx4 v[120:123], v[64:65], off offset:1024
	global_load_dwordx4 v[202:205], v[66:67], off offset:160
	global_load_dwordx4 v[92:95], v[60:61], off offset:192
	global_load_dwordx4 v[124:127], v[64:65], off offset:2048
	global_load_dwordx4 v[206:209], v[66:67], off offset:192
	global_load_dwordx4 v[96:99], v[60:61], off offset:224
	global_load_dwordx4 v[128:131], v[64:65], off offset:3072
	global_load_dwordx4 v[210:213], v[66:67], off offset:224
	v_lshl_add_u64 v[60:61], s[58:59], 0, v[62:63]
	v_add_u32_e32 v56, s3, v44
	v_or_b32_e32 v58, v56, v34
	v_ashrrev_i32_e32 v59, 31, v58
	v_lshl_add_u64 v[58:59], v[58:59], 1, v[60:61]
	v_ashrrev_i32_e32 v57, 31, v56
	v_lshl_add_u64 v[216:217], v[56:57], 0, v[34:35]
	v_lshl_add_u64 v[216:217], v[216:217], 1, v[60:61]
	global_load_dword v214, v[58:59], off
	global_load_dword v215, v[216:217], off offset:64
	s_waitcnt vmcnt(23)
	v_mfma_f32_32x32x16_bf16 v[2:17], v[68:71], v[100:103], 0
	v_mfma_f32_32x32x16_bf16 v[18:33], v[182:185], v[100:103], 0
	s_waitcnt vmcnt(20)
	v_mfma_f32_32x32x16_bf16 v[2:17], v[72:75], v[104:107], v[2:17]
	v_mfma_f32_32x32x16_bf16 v[18:33], v[186:189], v[104:107], v[18:33]
	s_waitcnt vmcnt(17)
	v_mfma_f32_32x32x16_bf16 v[2:17], v[76:79], v[108:111], v[2:17]
	v_mfma_f32_32x32x16_bf16 v[18:33], v[190:193], v[108:111], v[18:33]
	s_waitcnt vmcnt(14)
	v_mfma_f32_32x32x16_bf16 v[2:17], v[80:83], v[112:115], v[2:17]
	v_mfma_f32_32x32x16_bf16 v[18:33], v[194:197], v[112:115], v[18:33]
	s_waitcnt vmcnt(11)
	v_mfma_f32_32x32x16_bf16 v[2:17], v[84:87], v[116:119], v[2:17]
	v_mfma_f32_32x32x16_bf16 v[18:33], v[198:201], v[116:119], v[18:33]
	s_waitcnt vmcnt(8)
	v_mfma_f32_32x32x16_bf16 v[2:17], v[88:91], v[120:123], v[2:17]
	v_mfma_f32_32x32x16_bf16 v[18:33], v[202:205], v[120:123], v[18:33]
	s_waitcnt vmcnt(5)
	v_mfma_f32_32x32x16_bf16 v[2:17], v[92:95], v[124:127], v[2:17]
	v_mfma_f32_32x32x16_bf16 v[18:33], v[206:209], v[124:127], v[18:33]
	s_waitcnt vmcnt(2)
	v_mfma_f32_32x32x16_bf16 v[2:17], v[96:99], v[128:131], v[2:17]
	v_mfma_f32_32x32x16_bf16 v[18:33], v[210:213], v[128:131], v[18:33]
	s_nop 7
	s_nop 4
	ds_write2st64_b32 v46, v2, v3 offset1:1
	ds_write2st64_b32 v46, v4, v5 offset0:2 offset1:3
	ds_write2st64_b32 v46, v6, v7 offset0:4 offset1:5
	ds_write2st64_b32 v46, v8, v9 offset0:6 offset1:7
	ds_write2st64_b32 v46, v10, v11 offset0:8 offset1:9
	ds_write2st64_b32 v46, v12, v13 offset0:10 offset1:11
	ds_write2st64_b32 v46, v14, v15 offset0:12 offset1:13
	ds_write2st64_b32 v46, v16, v17 offset0:14 offset1:15
	ds_write2st64_b32 v46, v18, v19 offset0:16 offset1:17
	ds_write2st64_b32 v46, v20, v21 offset0:18 offset1:19
	ds_write2st64_b32 v46, v22, v23 offset0:20 offset1:21
	ds_write2st64_b32 v46, v24, v25 offset0:22 offset1:23
	ds_write2st64_b32 v46, v26, v27 offset0:24 offset1:25
	ds_write2st64_b32 v46, v28, v29 offset0:26 offset1:27
	ds_write2st64_b32 v46, v30, v31 offset0:28 offset1:29
	ds_write2st64_b32 v46, v32, v33 offset0:30 offset1:31
	s_waitcnt lgkmcnt(0)
	s_barrier
	v_lshl_add_u64 v[2:3], v[56:57], 0, v[34:35]
	v_lshl_add_u64 v[4:5], v[2:3], 1, v[60:61]
	ds_read2st64_b32 v[2:3], v47 offset1:1
	ds_read2st64_b32 v[6:7], v47 offset0:32 offset1:33
	ds_read2st64_b32 v[8:9], v47 offset0:64 offset1:65
	ds_read2st64_b32 v[10:11], v47 offset0:96 offset1:97
	ds_read2st64_b32 v[12:13], v47 offset0:128 offset1:129
	ds_read2st64_b32 v[14:15], v47 offset0:160 offset1:161
	ds_read2st64_b32 v[16:17], v47 offset0:192 offset1:193
	ds_read2st64_b32 v[18:19], v47 offset0:224 offset1:225
	s_waitcnt lgkmcnt(7)
	v_pk_add_f32 v[2:3], v[2:3], 0 op_sel_hi:[1,0]
	s_waitcnt lgkmcnt(6)
	v_pk_add_f32 v[2:3], v[2:3], v[6:7]
	s_waitcnt vmcnt(0)
	v_and_b32_e32 v7, 0xffff0000, v214
	s_waitcnt lgkmcnt(5)
	v_pk_add_f32 v[2:3], v[2:3], v[8:9]
	v_lshlrev_b32_e32 v6, 16, v214
	s_waitcnt lgkmcnt(4)
	v_pk_add_f32 v[2:3], v[2:3], v[10:11]
	s_waitcnt lgkmcnt(3)
	v_pk_add_f32 v[2:3], v[2:3], v[12:13]
	s_waitcnt lgkmcnt(2)
	v_pk_add_f32 v[2:3], v[2:3], v[14:15]
	s_waitcnt lgkmcnt(1)
	v_pk_add_f32 v[2:3], v[2:3], v[16:17]
	s_waitcnt lgkmcnt(0)
	v_pk_add_f32 v[2:3], v[2:3], v[18:19]
	s_nop 0
	v_pk_add_f32 v[2:3], v[2:3], v[6:7]
	s_nop 0
	v_and_b32_sdwa v6, v3, v180 dst_sel:DWORD dst_unused:UNUSED_PAD src0_sel:WORD_1 src1_sel:DWORD
	v_and_b32_sdwa v7, v2, v180 dst_sel:DWORD dst_unused:UNUSED_PAD src0_sel:WORD_1 src1_sel:DWORD
	v_add3_u32 v7, v2, v7, s15
	v_add3_u32 v6, v3, v6, s15
	v_perm_b32 v6, v6, v7, s2
	global_store_dword v[58:59], v6, off sc1
	ds_read2st64_b32 v[6:7], v47 offset0:48 offset1:49
	ds_read2st64_b32 v[8:9], v47 offset0:16 offset1:17
	ds_read2st64_b32 v[10:11], v47 offset0:112 offset1:113
	ds_read2st64_b32 v[12:13], v47 offset0:80 offset1:81
	ds_read2st64_b32 v[14:15], v47 offset0:176 offset1:177
	ds_read2st64_b32 v[16:17], v47 offset0:144 offset1:145
	ds_read2st64_b32 v[18:19], v47 offset0:240 offset1:241
	ds_read2st64_b32 v[20:21], v47 offset0:208 offset1:209
	s_waitcnt lgkmcnt(6)
	v_pk_add_f32 v[8:9], v[8:9], 0 op_sel_hi:[1,0]
	v_pk_mul_f32 v[2:3], v[2:3], v[2:3]
	v_pk_add_f32 v[6:7], v[8:9], v[6:7]
	v_add_f32_e32 v8, v2, v3
	s_waitcnt lgkmcnt(4)
	v_pk_add_f32 v[6:7], v[6:7], v[12:13]
	v_and_b32_e32 v3, 0xffff0000, v215
	v_pk_add_f32 v[6:7], v[6:7], v[10:11]
	v_lshlrev_b32_e32 v2, 16, v215
	s_waitcnt lgkmcnt(2)
	v_pk_add_f32 v[6:7], v[6:7], v[16:17]
	s_nop 0
	v_pk_add_f32 v[6:7], v[6:7], v[14:15]
	s_waitcnt lgkmcnt(0)
	v_pk_add_f32 v[6:7], v[6:7], v[20:21]
	s_nop 0
	v_pk_add_f32 v[6:7], v[6:7], v[18:19]
	s_nop 0
	v_pk_add_f32 v[6:7], v[6:7], v[2:3]
	s_nop 0
	v_pk_mul_f32 v[2:3], v[6:7], v[6:7]
	v_and_b32_sdwa v9, v7, v180 dst_sel:DWORD dst_unused:UNUSED_PAD src0_sel:WORD_1 src1_sel:DWORD
	v_add_f32_e32 v2, v8, v2
	v_add_f32_e32 v2, v2, v3
	ds_bpermute_b32 v3, v45, v2
	v_and_b32_sdwa v8, v6, v180 dst_sel:DWORD dst_unused:UNUSED_PAD src0_sel:WORD_1 src1_sel:DWORD
	v_add3_u32 v6, v6, v8, s15
	v_add3_u32 v7, v7, v9, s15
	v_perm_b32 v6, v7, v6, s2
	global_store_dword v[4:5], v6, off offset:64 sc1
	s_and_saveexec_b64 s[2:3], s[40:41]
	s_cbranch_execz .LBB0_920
	v_lshl_add_u64 v[4:5], v[40:41], 2, s[0:1]
	s_waitcnt lgkmcnt(0)
	v_add_f32_e32 v2, v2, v3
	global_atomic_add_f32 v[4:5], v2, off
	s_branch .LBB0_920

.LBB0_959:
	s_and_b32 s3, s5, 0x3c0
	v_or_b32_e32 v2, s3, v43
	v_lshlrev_b32_e32 v154, 11, v2
	s_and_b32 s2, s4, 0xffffffe0
	v_lshl_add_u64 v[60:61], v[38:39], 0, v[154:155]
	v_add_u32_e32 v40, s2, v42
	v_ashrrev_i32_e32 v41, 31, v40
	v_lshlrev_b64 v[62:63], 11, v[40:41]
	v_lshl_add_u64 v[64:65], v[36:37], 0, v[62:63]
	s_mov_b32 s2, 0x10000
	v_add_co_u32_e32 v66, vcc, s2, v60
	s_mov_b32 s2, 0x7060302
	s_nop 0
	v_addc_co_u32_e32 v67, vcc, 0, v61, vcc
	v_lshrrev_b32_e64 v64, 4, s6
	v_lshrrev_b32_e32 v65, 6, v0
	v_lshl_add_u32 v64, v64, 3, v65
	v_lshlrev_b32_e32 v64, 13, v64
	v_and_b32_e32 v65, 63, v0
	v_lshl_add_u32 v64, v65, 4, v64
	v_add_u32_e32 v64, 0x2001000, v64
	v_mov_b32_e32 v65, 0
	v_lshl_add_u64 v[64:65], s[62:63], 0, v[64:65]
	global_load_dwordx4 v[68:71], v[60:61], off
	global_load_dwordx4 v[100:103], v[64:65], off offset:-4096
	global_load_dwordx4 v[182:185], v[66:67], off
	global_load_dwordx4 v[72:75], v[60:61], off offset:32
	global_load_dwordx4 v[104:107], v[64:65], off offset:-3072
	global_load_dwordx4 v[186:189], v[66:67], off offset:32
	global_load_dwordx4 v[76:79], v[60:61], off offset:64
	global_load_dwordx4 v[108:111], v[64:65], off offset:-2048
	global_load_dwordx4 v[190:193], v[66:67], off offset:64
	global_load_dwordx4 v[80:83], v[60:61], off offset:96
	global_load_dwordx4 v[112:115], v[64:65], off offset:-1024
	global_load_dwordx4 v[194:197], v[66:67], off offset:96
	global_load_dwordx4 v[84:87], v[60:61], off offset:128
	global_load_dwordx4 v[116:119], v[64:65], off
	global_load_dwordx4 v[198:201], v[66:67], off offset:128
	global_load_dwordx4 v[88:91], v[60:61], off offset:160
	global_load_dwordx4 v[120:123], v[64:65], off offset:1024
	global_load_dwordx4 v[202:205], v[66:67], off offset:160
	global_load_dwordx4 v[92:95], v[60:61], off offset:192
	global_load_dwordx4 v[124:127], v[64:65], off offset:2048
	global_load_dwordx4 v[206:209], v[66:67], off offset:192
	global_load_dwordx4 v[96:99], v[60:61], off offset:224
	global_load_dwordx4 v[128:131], v[64:65], off offset:3072
	global_load_dwordx4 v[210:213], v[66:67], off offset:224
	v_lshl_add_u64 v[60:61], s[58:59], 0, v[62:63]
	v_add_u32_e32 v56, s3, v44
	v_or_b32_e32 v58, v56, v34
	v_ashrrev_i32_e32 v59, 31, v58
	v_lshl_add_u64 v[58:59], v[58:59], 1, v[60:61]
	v_ashrrev_i32_e32 v57, 31, v56
	v_lshl_add_u64 v[216:217], v[56:57], 0, v[34:35]
	v_lshl_add_u64 v[216:217], v[216:217], 1, v[60:61]
	global_load_dword v214, v[58:59], off
	global_load_dword v215, v[216:217], off offset:64
	s_waitcnt vmcnt(23)
	v_mfma_f32_32x32x16_bf16 v[2:17], v[68:71], v[100:103], 0
	v_mfma_f32_32x32x16_bf16 v[18:33], v[182:185], v[100:103], 0
	s_waitcnt vmcnt(20)
	v_mfma_f32_32x32x16_bf16 v[2:17], v[72:75], v[104:107], v[2:17]
	v_mfma_f32_32x32x16_bf16 v[18:33], v[186:189], v[104:107], v[18:33]
	s_waitcnt vmcnt(17)
	v_mfma_f32_32x32x16_bf16 v[2:17], v[76:79], v[108:111], v[2:17]
	v_mfma_f32_32x32x16_bf16 v[18:33], v[190:193], v[108:111], v[18:33]
	s_waitcnt vmcnt(14)
	v_mfma_f32_32x32x16_bf16 v[2:17], v[80:83], v[112:115], v[2:17]
	v_mfma_f32_32x32x16_bf16 v[18:33], v[194:197], v[112:115], v[18:33]
	s_waitcnt vmcnt(11)
	v_mfma_f32_32x32x16_bf16 v[2:17], v[84:87], v[116:119], v[2:17]
	v_mfma_f32_32x32x16_bf16 v[18:33], v[198:201], v[116:119], v[18:33]
	s_waitcnt vmcnt(8)
	v_mfma_f32_32x32x16_bf16 v[2:17], v[88:91], v[120:123], v[2:17]
	v_mfma_f32_32x32x16_bf16 v[18:33], v[202:205], v[120:123], v[18:33]
	s_waitcnt vmcnt(5)
	v_mfma_f32_32x32x16_bf16 v[2:17], v[92:95], v[124:127], v[2:17]
	v_mfma_f32_32x32x16_bf16 v[18:33], v[206:209], v[124:127], v[18:33]
	s_waitcnt vmcnt(2)
	v_mfma_f32_32x32x16_bf16 v[2:17], v[96:99], v[128:131], v[2:17]
	v_mfma_f32_32x32x16_bf16 v[18:33], v[210:213], v[128:131], v[18:33]
	s_nop 7
	s_nop 4
	ds_write2st64_b32 v46, v2, v3 offset1:1
	ds_write2st64_b32 v46, v4, v5 offset0:2 offset1:3
	ds_write2st64_b32 v46, v6, v7 offset0:4 offset1:5
	ds_write2st64_b32 v46, v8, v9 offset0:6 offset1:7
	ds_write2st64_b32 v46, v10, v11 offset0:8 offset1:9
	ds_write2st64_b32 v46, v12, v13 offset0:10 offset1:11
	ds_write2st64_b32 v46, v14, v15 offset0:12 offset1:13
	ds_write2st64_b32 v46, v16, v17 offset0:14 offset1:15
	ds_write2st64_b32 v46, v18, v19 offset0:16 offset1:17
	ds_write2st64_b32 v46, v20, v21 offset0:18 offset1:19
	ds_write2st64_b32 v46, v22, v23 offset0:20 offset1:21
	ds_write2st64_b32 v46, v24, v25 offset0:22 offset1:23
	ds_write2st64_b32 v46, v26, v27 offset0:24 offset1:25
	ds_write2st64_b32 v46, v28, v29 offset0:26 offset1:27
	ds_write2st64_b32 v46, v30, v31 offset0:28 offset1:29
	ds_write2st64_b32 v46, v32, v33 offset0:30 offset1:31
	s_waitcnt lgkmcnt(0)
	s_barrier
	v_lshl_add_u64 v[2:3], v[56:57], 0, v[34:35]
	v_lshl_add_u64 v[4:5], v[2:3], 1, v[60:61]
	ds_read2st64_b32 v[2:3], v47 offset1:1
	ds_read2st64_b32 v[6:7], v47 offset0:32 offset1:33
	ds_read2st64_b32 v[8:9], v47 offset0:64 offset1:65
	ds_read2st64_b32 v[10:11], v47 offset0:96 offset1:97
	ds_read2st64_b32 v[12:13], v47 offset0:128 offset1:129
	ds_read2st64_b32 v[14:15], v47 offset0:160 offset1:161
	ds_read2st64_b32 v[16:17], v47 offset0:192 offset1:193
	ds_read2st64_b32 v[18:19], v47 offset0:224 offset1:225
	s_waitcnt lgkmcnt(7)
	v_pk_add_f32 v[2:3], v[2:3], 0 op_sel_hi:[1,0]
	s_waitcnt lgkmcnt(6)
	v_pk_add_f32 v[2:3], v[2:3], v[6:7]
	s_waitcnt vmcnt(0)
	v_and_b32_e32 v7, 0xffff0000, v214
	s_waitcnt lgkmcnt(5)
	v_pk_add_f32 v[2:3], v[2:3], v[8:9]
	v_lshlrev_b32_e32 v6, 16, v214
	s_waitcnt lgkmcnt(4)
	v_pk_add_f32 v[2:3], v[2:3], v[10:11]
	s_waitcnt lgkmcnt(3)
	v_pk_add_f32 v[2:3], v[2:3], v[12:13]
	s_waitcnt lgkmcnt(2)
	v_pk_add_f32 v[2:3], v[2:3], v[14:15]
	s_waitcnt lgkmcnt(1)
	v_pk_add_f32 v[2:3], v[2:3], v[16:17]
	s_waitcnt lgkmcnt(0)
	v_pk_add_f32 v[2:3], v[2:3], v[18:19]
	s_nop 0
	v_pk_add_f32 v[2:3], v[2:3], v[6:7]
	s_nop 0
	v_and_b32_sdwa v6, v3, v180 dst_sel:DWORD dst_unused:UNUSED_PAD src0_sel:WORD_1 src1_sel:DWORD
	v_and_b32_sdwa v7, v2, v180 dst_sel:DWORD dst_unused:UNUSED_PAD src0_sel:WORD_1 src1_sel:DWORD
	v_add3_u32 v7, v2, v7, s15
	v_add3_u32 v6, v3, v6, s15
	v_perm_b32 v6, v6, v7, s2
	global_store_dword v[58:59], v6, off sc1
	ds_read2st64_b32 v[6:7], v47 offset0:48 offset1:49
	ds_read2st64_b32 v[8:9], v47 offset0:16 offset1:17
	ds_read2st64_b32 v[10:11], v47 offset0:112 offset1:113
	ds_read2st64_b32 v[12:13], v47 offset0:80 offset1:81
	ds_read2st64_b32 v[14:15], v47 offset0:176 offset1:177
	ds_read2st64_b32 v[16:17], v47 offset0:144 offset1:145
	ds_read2st64_b32 v[18:19], v47 offset0:240 offset1:241
	ds_read2st64_b32 v[20:21], v47 offset0:208 offset1:209
	s_waitcnt lgkmcnt(6)
	v_pk_add_f32 v[8:9], v[8:9], 0 op_sel_hi:[1,0]
	v_pk_mul_f32 v[2:3], v[2:3], v[2:3]
	v_pk_add_f32 v[6:7], v[8:9], v[6:7]
	v_add_f32_e32 v8, v2, v3
	s_waitcnt lgkmcnt(4)
	v_pk_add_f32 v[6:7], v[6:7], v[12:13]
	v_and_b32_e32 v3, 0xffff0000, v215
	v_pk_add_f32 v[6:7], v[6:7], v[10:11]
	v_lshlrev_b32_e32 v2, 16, v215
	s_waitcnt lgkmcnt(2)
	v_pk_add_f32 v[6:7], v[6:7], v[16:17]
	s_nop 0
	v_pk_add_f32 v[6:7], v[6:7], v[14:15]
	s_waitcnt lgkmcnt(0)
	v_pk_add_f32 v[6:7], v[6:7], v[20:21]
	s_nop 0
	v_pk_add_f32 v[6:7], v[6:7], v[18:19]
	s_nop 0
	v_pk_add_f32 v[6:7], v[6:7], v[2:3]
	s_nop 0
	v_pk_mul_f32 v[2:3], v[6:7], v[6:7]
	v_and_b32_sdwa v9, v7, v180 dst_sel:DWORD dst_unused:UNUSED_PAD src0_sel:WORD_1 src1_sel:DWORD
	v_add_f32_e32 v2, v8, v2
	v_add_f32_e32 v2, v2, v3
	ds_bpermute_b32 v3, v45, v2
	v_and_b32_sdwa v8, v6, v180 dst_sel:DWORD dst_unused:UNUSED_PAD src0_sel:WORD_1 src1_sel:DWORD
	v_add3_u32 v6, v6, v8, s15
	v_add3_u32 v7, v7, v9, s15
	v_perm_b32 v6, v7, v6, s2
	global_store_dword v[4:5], v6, off offset:64 sc1
	s_and_saveexec_b64 s[2:3], s[36:37]
	s_cbranch_execz .LBB0_958
	v_lshl_add_u64 v[4:5], v[40:41], 2, s[0:1]
	s_waitcnt lgkmcnt(0)
	v_add_f32_e32 v2, v2, v3
	global_atomic_add_f32 v[4:5], v2, off
	s_branch .LBB0_958
